# gate GEMM epilogue: store addresses as first address plus constant offsets
# baseline (speedup 1.0000x reference)
; #define EPI8(...) \
;     _Pragma("unroll") for (int ai = 0; ai < 2; ++ai) _Pragma("unroll") for (int m = 0; m < 4; ++m) { const int row = u.pm * 256 + ai * 128 + wr * 64 + m * 16 + fr; \
;     _Pragma("unroll") for (int bj = 0; bj < 2; ++bj) { const int c8 = bj * 128 + wc * 32 + fq * 8; const f32x4 v0 = acc[ai][bj][m][0], v1 = acc[ai][bj][m][1]; __VA_ARGS__ } }
; __device__ __forceinline__ u32x4v pack8(f32x4 a, f32x4 b) { u32x4v o; o.x = cvt_pk_bf16(a[0], a[1]); o.y = cvt_pk_bf16(a[2], a[3]); o.z = cvt_pk_bf16(b[0], b[1]); o.w = cvt_pk_bf16(b[2], b[3]); return o; }
; __device__ __forceinline__ f32x4 sig4(f32x4 v) { return (f32x4){sigm(v[0]), sigm(v[1]), sigm(v[2]), sigm(v[3])}; }
;     __device__ __forceinline__ void operator()(const f32x4 (&acc)[2][2][4][2], const pg8::Unit& u, int wr, int wc, int fr, int fq) const {
;         EPI8( *(u32x4v*)(O + (size_t)row * ldc + u.pn * 256 + c8) = pack8(sig4(v0), sig4(v1)); )
;     }
.LBB0_1249:
	v_mul_f32_e32 v126, 0xbfb8aa3b, v126
	v_mul_f32_e32 v127, 0xbfb8aa3b, v127
	v_mul_f32_e32 v122, 0xbfb8aa3b, v122
	v_mul_f32_e32 v123, 0xbfb8aa3b, v123
	v_exp_f32_e32 v126, v126
	v_exp_f32_e32 v127, v127
	v_mul_f32_e32 v128, 0xbfb8aa3b, v128
	v_mul_f32_e32 v129, 0xbfb8aa3b, v129
	v_exp_f32_e32 v122, v122
	v_exp_f32_e32 v123, v123
	v_exp_f32_e32 v128, v128
	v_exp_f32_e32 v129, v129
	v_mul_f32_e32 v124, 0xbfb8aa3b, v124
	v_exp_f32_e32 v124, v124
	v_mul_f32_e32 v125, 0xbfb8aa3b, v125
	v_exp_f32_e32 v125, v125
	v_add_f32_e32 v126, 1.0, v126
	v_add_f32_e32 v127, 1.0, v127
	v_add_f32_e32 v122, 1.0, v122
	v_add_f32_e32 v123, 1.0, v123
	v_rcp_f32_e32 v126, v126
	v_rcp_f32_e32 v127, v127
	v_add_f32_e32 v128, 1.0, v128
	v_add_f32_e32 v129, 1.0, v129
	v_rcp_f32_e32 v122, v122
	v_rcp_f32_e32 v123, v123
	v_rcp_f32_e32 v128, v128
	v_rcp_f32_e32 v129, v129
	v_add_f32_e32 v124, 1.0, v124
	v_rcp_f32_e32 v146, v124
	v_add_f32_e32 v124, 1.0, v125
	v_readlane_b32 s16, v252, 35
	v_mul_f32_e32 v114, 0xbfb8aa3b, v114
	s_lshl_b32 s14, s28, 8
	v_rcp_f32_e32 v147, v124
	v_readlane_b32 s17, v252, 36
	v_exp_f32_e32 v114, v114
	v_mul_f32_e32 v115, 0xbfb8aa3b, v115
	v_lshl_add_u32 v145, s29, 8, v142
	s_ashr_i32 s15, s14, 31
	v_cvt_pk_bf16_f32 v124, v126, v127
	v_cvt_pk_bf16_f32 v126, v122, v123
	v_mov_b64_e32 v[122:123], s[16:17]
	s_movk_i32 s7, 0x1800
	v_exp_f32_e32 v115, v115
	v_cvt_pk_bf16_f32 v125, v128, v129
	v_mad_i64_i32 v[128:129], s[16:17], v145, s7, v[122:123]
	s_lshl_b64 s[14:15], s[14:15], 1
	v_lshl_add_u64 v[128:129], v[128:129], 0, s[14:15]
	v_cvt_pk_bf16_f32 v127, v146, v147
	v_lshl_add_u64 v[128:129], v[128:129], 0, v[0:1]
	v_add_f32_e32 v114, 1.0, v114
	global_store_dwordx4 v[128:129], v[124:127], off
	v_mul_f32_e32 v118, 0xbfb8aa3b, v118
	v_mul_f32_e32 v119, 0xbfb8aa3b, v119
	v_rcp_f32_e32 v124, v114
	v_add_f32_e32 v114, 1.0, v115
	v_mul_f32_e32 v115, 0xbfb8aa3b, v116
	v_mul_f32_e32 v120, 0xbfb8aa3b, v120
	v_mul_f32_e32 v121, 0xbfb8aa3b, v121
	v_exp_f32_e32 v115, v115
	v_mul_f32_e32 v116, 0xbfb8aa3b, v117
	v_exp_f32_e32 v118, v118
	v_exp_f32_e32 v119, v119
	v_exp_f32_e32 v120, v120
	v_exp_f32_e32 v121, v121
	v_exp_f32_e32 v116, v116
	v_rcp_f32_e32 v117, v114
	v_add_f32_e32 v114, 1.0, v115
	v_add_f32_e32 v118, 1.0, v118
	v_add_f32_e32 v119, 1.0, v119
	v_add_f32_e32 v120, 1.0, v120
	v_add_f32_e32 v121, 1.0, v121
	v_rcp_f32_e32 v125, v114
	v_add_f32_e32 v114, 1.0, v116
	v_mul_f32_e32 v106, 0xbfb8aa3b, v106
	v_rcp_f32_e32 v118, v118
	v_rcp_f32_e32 v119, v119
	v_rcp_f32_e32 v120, v120
	v_rcp_f32_e32 v121, v121
	v_rcp_f32_e32 v126, v114
	v_exp_f32_e32 v106, v106
	v_mul_f32_e32 v107, 0xbfb8aa3b, v107
	v_exp_f32_e32 v107, v107
	v_cvt_pk_bf16_f32 v114, v118, v119
	v_cvt_pk_bf16_f32 v115, v120, v121
	v_cvt_pk_bf16_f32 v116, v124, v117
	v_cvt_pk_bf16_f32 v117, v125, v126
	v_mul_f32_e32 v110, 0xbfb8aa3b, v110
	v_mul_f32_e32 v111, 0xbfb8aa3b, v111
	v_add_f32_e32 v106, 1.0, v106
	global_store_dwordx4 v[128:129], v[114:117], off offset:256
	v_exp_f32_e32 v110, v110
	v_exp_f32_e32 v111, v111
	v_rcp_f32_e32 v115, v106
	v_add_f32_e32 v106, 1.0, v107
	v_mul_f32_e32 v107, 0xbfb8aa3b, v108
	v_mul_f32_e32 v112, 0xbfb8aa3b, v112
	v_mul_f32_e32 v113, 0xbfb8aa3b, v113
	v_exp_f32_e32 v107, v107
	v_mul_f32_e32 v108, 0xbfb8aa3b, v109
	v_exp_f32_e32 v112, v112
	v_exp_f32_e32 v113, v113
	v_exp_f32_e32 v108, v108
	v_add_f32_e32 v110, 1.0, v110
	v_add_f32_e32 v111, 1.0, v111
	v_rcp_f32_e32 v110, v110
	v_rcp_f32_e32 v111, v111
	v_rcp_f32_e32 v109, v106
	v_add_f32_e32 v106, 1.0, v107
	v_add_f32_e32 v112, 1.0, v112
	v_add_f32_e32 v113, 1.0, v113
	v_rcp_f32_e32 v116, v106
	v_add_f32_e32 v106, 1.0, v108
	v_mul_f32_e32 v98, 0xbfb8aa3b, v98
	v_rcp_f32_e32 v112, v112
	v_rcp_f32_e32 v113, v113
	v_rcp_f32_e32 v117, v106
	v_exp_f32_e32 v98, v98
	v_mul_f32_e32 v99, 0xbfb8aa3b, v99
	v_exp_f32_e32 v99, v99
	v_cvt_pk_bf16_f32 v106, v110, v111
	v_cvt_pk_bf16_f32 v107, v112, v113
	v_cvt_pk_bf16_f32 v108, v115, v109
	v_cvt_pk_bf16_f32 v109, v116, v117
	s_mov_b32 s16, 0x18000
	s_mov_b32 s17, 0
	v_lshl_add_u64 v[110:111], s[16:17], 0, v[128:129]
	v_add_f32_e32 v98, 1.0, v98
	global_store_dwordx4 v[110:111], v[106:109], off
	v_mul_f32_e32 v102, 0xbfb8aa3b, v102
	v_mul_f32_e32 v103, 0xbfb8aa3b, v103
	v_rcp_f32_e32 v106, v98
	v_add_f32_e32 v98, 1.0, v99
	v_mul_f32_e32 v99, 0xbfb8aa3b, v100
	v_mul_f32_e32 v104, 0xbfb8aa3b, v104
	v_mul_f32_e32 v105, 0xbfb8aa3b, v105
	v_exp_f32_e32 v99, v99
	v_mul_f32_e32 v100, 0xbfb8aa3b, v101
	v_exp_f32_e32 v102, v102
	v_exp_f32_e32 v103, v103
	v_exp_f32_e32 v104, v104
	v_exp_f32_e32 v105, v105
	v_exp_f32_e32 v100, v100
	v_rcp_f32_e32 v101, v98
	v_add_f32_e32 v98, 1.0, v99
	v_add_f32_e32 v102, 1.0, v102
	v_add_f32_e32 v103, 1.0, v103
	v_add_f32_e32 v104, 1.0, v104
	v_add_f32_e32 v105, 1.0, v105
	v_rcp_f32_e32 v107, v98
	v_add_f32_e32 v98, 1.0, v100
	v_mul_f32_e32 v90, 0xbfb8aa3b, v90
	v_rcp_f32_e32 v102, v102
	v_rcp_f32_e32 v103, v103
	v_rcp_f32_e32 v104, v104
	v_rcp_f32_e32 v105, v105
	v_rcp_f32_e32 v108, v98
	v_exp_f32_e32 v90, v90
	v_mul_f32_e32 v91, 0xbfb8aa3b, v91
	v_exp_f32_e32 v91, v91
	v_cvt_pk_bf16_f32 v98, v102, v103
	v_cvt_pk_bf16_f32 v99, v104, v105
	v_cvt_pk_bf16_f32 v100, v106, v101
	v_cvt_pk_bf16_f32 v101, v107, v108
	v_mul_f32_e32 v94, 0xbfb8aa3b, v94
	v_mul_f32_e32 v95, 0xbfb8aa3b, v95
	v_add_f32_e32 v90, 1.0, v90
	global_store_dwordx4 v[110:111], v[98:101], off offset:256
	v_exp_f32_e32 v94, v94
	v_exp_f32_e32 v95, v95
	v_rcp_f32_e32 v99, v90
	v_add_f32_e32 v90, 1.0, v91
	v_mul_f32_e32 v91, 0xbfb8aa3b, v92
	v_mul_f32_e32 v96, 0xbfb8aa3b, v96
	v_mul_f32_e32 v97, 0xbfb8aa3b, v97
	v_exp_f32_e32 v91, v91
	v_mul_f32_e32 v92, 0xbfb8aa3b, v93
; #define EPI8(...) \
;     _Pragma("unroll") for (int ai = 0; ai < 2; ++ai) _Pragma("unroll") for (int m = 0; m < 4; ++m) { const int row = u.pm * 256 + ai * 128 + wr * 64 + m * 16 + fr; \
;     _Pragma("unroll") for (int bj = 0; bj < 2; ++bj) { const int c8 = bj * 128 + wc * 32 + fq * 8; const f32x4 v0 = acc[ai][bj][m][0], v1 = acc[ai][bj][m][1]; __VA_ARGS__ } }
; __device__ __forceinline__ u32x4v pack8(f32x4 a, f32x4 b) { u32x4v o; o.x = cvt_pk_bf16(a[0], a[1]); o.y = cvt_pk_bf16(a[2], a[3]); o.z = cvt_pk_bf16(b[0], b[1]); o.w = cvt_pk_bf16(b[2], b[3]); return o; }
; __device__ __forceinline__ f32x4 sig4(f32x4 v) { return (f32x4){sigm(v[0]), sigm(v[1]), sigm(v[2]), sigm(v[3])}; }
;     __device__ __forceinline__ void operator()(const f32x4 (&acc)[2][2][4][2], const pg8::Unit& u, int wr, int wc, int fr, int fq) const {
;         EPI8( *(u32x4v*)(O + (size_t)row * ldc + u.pn * 256 + c8) = pack8(sig4(v0), sig4(v1)); )
;     }
	v_exp_f32_e32 v96, v96
	v_exp_f32_e32 v97, v97
	v_exp_f32_e32 v92, v92
	v_add_f32_e32 v94, 1.0, v94
	v_add_f32_e32 v95, 1.0, v95
	v_rcp_f32_e32 v94, v94
	v_rcp_f32_e32 v95, v95
	v_rcp_f32_e32 v93, v90
	v_add_f32_e32 v90, 1.0, v91
	v_add_f32_e32 v96, 1.0, v96
	v_add_f32_e32 v97, 1.0, v97
	v_rcp_f32_e32 v100, v90
	v_add_f32_e32 v90, 1.0, v92
	v_mul_f32_e32 v82, 0xbfb8aa3b, v82
	v_rcp_f32_e32 v96, v96
	v_rcp_f32_e32 v97, v97
	v_rcp_f32_e32 v101, v90
	v_exp_f32_e32 v82, v82
	v_mul_f32_e32 v83, 0xbfb8aa3b, v83
	v_exp_f32_e32 v83, v83
	v_cvt_pk_bf16_f32 v90, v94, v95
	v_cvt_pk_bf16_f32 v91, v96, v97
	v_cvt_pk_bf16_f32 v92, v99, v93
	v_cvt_pk_bf16_f32 v93, v100, v101
	s_mov_b32 s16, 0x30000
	s_mov_b32 s17, 0
	v_lshl_add_u64 v[94:95], s[16:17], 0, v[128:129]
	v_add_f32_e32 v82, 1.0, v82
	global_store_dwordx4 v[94:95], v[90:93], off
	v_mul_f32_e32 v86, 0xbfb8aa3b, v86
	v_mul_f32_e32 v87, 0xbfb8aa3b, v87
	v_rcp_f32_e32 v90, v82
	v_add_f32_e32 v82, 1.0, v83
	v_mul_f32_e32 v83, 0xbfb8aa3b, v84
	v_mul_f32_e32 v88, 0xbfb8aa3b, v88
	v_mul_f32_e32 v89, 0xbfb8aa3b, v89
	v_exp_f32_e32 v83, v83
	v_mul_f32_e32 v84, 0xbfb8aa3b, v85
	v_exp_f32_e32 v86, v86
	v_exp_f32_e32 v87, v87
	v_exp_f32_e32 v88, v88
	v_exp_f32_e32 v89, v89
	v_exp_f32_e32 v84, v84
	v_rcp_f32_e32 v85, v82
	v_add_f32_e32 v82, 1.0, v83
	v_add_f32_e32 v86, 1.0, v86
	v_add_f32_e32 v87, 1.0, v87
	v_add_f32_e32 v88, 1.0, v88
	v_add_f32_e32 v89, 1.0, v89
	v_rcp_f32_e32 v91, v82
	v_add_f32_e32 v82, 1.0, v84
	v_mul_f32_e32 v74, 0xbfb8aa3b, v74
	v_rcp_f32_e32 v86, v86
	v_rcp_f32_e32 v87, v87
	v_rcp_f32_e32 v88, v88
	v_rcp_f32_e32 v89, v89
	v_rcp_f32_e32 v92, v82
	v_exp_f32_e32 v74, v74
	v_mul_f32_e32 v75, 0xbfb8aa3b, v75
	v_exp_f32_e32 v75, v75
	v_cvt_pk_bf16_f32 v82, v86, v87
	v_cvt_pk_bf16_f32 v83, v88, v89
	v_cvt_pk_bf16_f32 v84, v90, v85
	v_cvt_pk_bf16_f32 v85, v91, v92
	v_mul_f32_e32 v78, 0xbfb8aa3b, v78
	v_mul_f32_e32 v79, 0xbfb8aa3b, v79
	v_add_f32_e32 v74, 1.0, v74
	global_store_dwordx4 v[94:95], v[82:85], off offset:256
	v_exp_f32_e32 v78, v78
	v_exp_f32_e32 v79, v79
	v_rcp_f32_e32 v83, v74
	v_add_f32_e32 v74, 1.0, v75
	v_mul_f32_e32 v75, 0xbfb8aa3b, v76
	v_mul_f32_e32 v80, 0xbfb8aa3b, v80
	v_mul_f32_e32 v81, 0xbfb8aa3b, v81
	v_exp_f32_e32 v75, v75
	v_mul_f32_e32 v76, 0xbfb8aa3b, v77
	v_exp_f32_e32 v80, v80
	v_exp_f32_e32 v81, v81
	v_exp_f32_e32 v76, v76
	v_add_f32_e32 v78, 1.0, v78
	v_add_f32_e32 v79, 1.0, v79
	v_rcp_f32_e32 v78, v78
	v_rcp_f32_e32 v79, v79
	v_rcp_f32_e32 v77, v74
	v_add_f32_e32 v74, 1.0, v75
	v_add_f32_e32 v80, 1.0, v80
	v_add_f32_e32 v81, 1.0, v81
	v_rcp_f32_e32 v84, v74
	v_add_f32_e32 v74, 1.0, v76
	v_mul_f32_e32 v66, 0xbfb8aa3b, v66
	v_rcp_f32_e32 v80, v80
	v_rcp_f32_e32 v81, v81
	v_rcp_f32_e32 v85, v74
	v_exp_f32_e32 v66, v66
	v_mul_f32_e32 v67, 0xbfb8aa3b, v67
	v_exp_f32_e32 v67, v67
	v_cvt_pk_bf16_f32 v74, v78, v79
	v_cvt_pk_bf16_f32 v75, v80, v81
	v_cvt_pk_bf16_f32 v76, v83, v77
	v_cvt_pk_bf16_f32 v77, v84, v85
	s_mov_b32 s16, 0x48000
	s_mov_b32 s17, 0
	v_lshl_add_u64 v[78:79], s[16:17], 0, v[128:129]
	v_add_f32_e32 v66, 1.0, v66
	global_store_dwordx4 v[78:79], v[74:77], off
	v_mul_f32_e32 v70, 0xbfb8aa3b, v70
	v_mul_f32_e32 v71, 0xbfb8aa3b, v71
	v_rcp_f32_e32 v74, v66
	v_add_f32_e32 v66, 1.0, v67
	v_mul_f32_e32 v67, 0xbfb8aa3b, v68
	v_mul_f32_e32 v72, 0xbfb8aa3b, v72
	v_mul_f32_e32 v73, 0xbfb8aa3b, v73
	v_exp_f32_e32 v67, v67
	v_mul_f32_e32 v68, 0xbfb8aa3b, v69
	v_exp_f32_e32 v70, v70
	v_exp_f32_e32 v71, v71
	v_exp_f32_e32 v72, v72
	v_exp_f32_e32 v73, v73
	v_exp_f32_e32 v68, v68
	v_rcp_f32_e32 v69, v66
	v_add_f32_e32 v66, 1.0, v67
	v_add_f32_e32 v70, 1.0, v70
	v_add_f32_e32 v71, 1.0, v71
	v_add_f32_e32 v72, 1.0, v72
	v_add_f32_e32 v73, 1.0, v73
	v_rcp_f32_e32 v75, v66
	v_add_f32_e32 v66, 1.0, v68
	v_mul_f32_e32 v58, 0xbfb8aa3b, v58
	v_rcp_f32_e32 v70, v70
	v_rcp_f32_e32 v71, v71
	v_rcp_f32_e32 v72, v72
	v_rcp_f32_e32 v73, v73
	v_rcp_f32_e32 v76, v66
	v_exp_f32_e32 v58, v58
	v_mul_f32_e32 v59, 0xbfb8aa3b, v59
	v_exp_f32_e32 v59, v59
	v_cvt_pk_bf16_f32 v66, v70, v71
	v_cvt_pk_bf16_f32 v67, v72, v73
	v_cvt_pk_bf16_f32 v68, v74, v69
	v_cvt_pk_bf16_f32 v69, v75, v76
	v_mul_f32_e32 v62, 0xbfb8aa3b, v62
	v_mul_f32_e32 v63, 0xbfb8aa3b, v63
	v_add_f32_e32 v58, 1.0, v58
	global_store_dwordx4 v[78:79], v[66:69], off offset:256
	v_exp_f32_e32 v62, v62
	v_exp_f32_e32 v63, v63
	v_rcp_f32_e32 v67, v58
	v_add_f32_e32 v58, 1.0, v59
	v_mul_f32_e32 v59, 0xbfb8aa3b, v60
	v_mul_f32_e32 v64, 0xbfb8aa3b, v64
	v_mul_f32_e32 v65, 0xbfb8aa3b, v65
	v_exp_f32_e32 v59, v59
	v_mul_f32_e32 v60, 0xbfb8aa3b, v61
	v_exp_f32_e32 v64, v64
	v_exp_f32_e32 v65, v65
	v_exp_f32_e32 v60, v60
	v_add_f32_e32 v62, 1.0, v62
	v_add_f32_e32 v63, 1.0, v63
	v_rcp_f32_e32 v62, v62
	v_rcp_f32_e32 v63, v63
	v_rcp_f32_e32 v61, v58
	v_add_f32_e32 v58, 1.0, v59
	v_add_f32_e32 v64, 1.0, v64
	v_add_f32_e32 v65, 1.0, v65
	v_rcp_f32_e32 v68, v58
	v_add_f32_e32 v58, 1.0, v60
	v_mul_f32_e32 v50, 0xbfb8aa3b, v50
	v_rcp_f32_e32 v64, v64
	v_rcp_f32_e32 v65, v65
	v_rcp_f32_e32 v69, v58
	v_exp_f32_e32 v50, v50
	v_mul_f32_e32 v51, 0xbfb8aa3b, v51
	v_exp_f32_e32 v51, v51
	v_cvt_pk_bf16_f32 v58, v62, v63
	v_cvt_pk_bf16_f32 v59, v64, v65
	v_cvt_pk_bf16_f32 v60, v67, v61
	v_cvt_pk_bf16_f32 v61, v68, v69
	s_mov_b32 s16, 0xc0000
	s_mov_b32 s17, 0
	v_lshl_add_u64 v[62:63], s[16:17], 0, v[128:129]
	v_add_f32_e32 v50, 1.0, v50
	global_store_dwordx4 v[62:63], v[58:61], off
	v_mul_f32_e32 v54, 0xbfb8aa3b, v54
	v_mul_f32_e32 v55, 0xbfb8aa3b, v55
	v_rcp_f32_e32 v58, v50
	v_add_f32_e32 v50, 1.0, v51
	v_mul_f32_e32 v51, 0xbfb8aa3b, v52
	v_mul_f32_e32 v56, 0xbfb8aa3b, v56
	v_mul_f32_e32 v57, 0xbfb8aa3b, v57
	v_exp_f32_e32 v51, v51
; #define EPI8(...) \
;     _Pragma("unroll") for (int ai = 0; ai < 2; ++ai) _Pragma("unroll") for (int m = 0; m < 4; ++m) { const int row = u.pm * 256 + ai * 128 + wr * 64 + m * 16 + fr; \
;     _Pragma("unroll") for (int bj = 0; bj < 2; ++bj) { const int c8 = bj * 128 + wc * 32 + fq * 8; const f32x4 v0 = acc[ai][bj][m][0], v1 = acc[ai][bj][m][1]; __VA_ARGS__ } }
; __device__ __forceinline__ u32x4v pack8(f32x4 a, f32x4 b) { u32x4v o; o.x = cvt_pk_bf16(a[0], a[1]); o.y = cvt_pk_bf16(a[2], a[3]); o.z = cvt_pk_bf16(b[0], b[1]); o.w = cvt_pk_bf16(b[2], b[3]); return o; }
; __device__ __forceinline__ f32x4 sig4(f32x4 v) { return (f32x4){sigm(v[0]), sigm(v[1]), sigm(v[2]), sigm(v[3])}; }
;     __device__ __forceinline__ void operator()(const f32x4 (&acc)[2][2][4][2], const pg8::Unit& u, int wr, int wc, int fr, int fq) const {
;         EPI8( *(u32x4v*)(O + (size_t)row * ldc + u.pn * 256 + c8) = pack8(sig4(v0), sig4(v1)); )
;     }
	v_mul_f32_e32 v52, 0xbfb8aa3b, v53
	v_exp_f32_e32 v54, v54
	v_exp_f32_e32 v55, v55
	v_exp_f32_e32 v56, v56
	v_exp_f32_e32 v57, v57
	v_exp_f32_e32 v52, v52
	v_rcp_f32_e32 v53, v50
	v_add_f32_e32 v50, 1.0, v51
	v_add_f32_e32 v54, 1.0, v54
	v_add_f32_e32 v55, 1.0, v55
	v_add_f32_e32 v56, 1.0, v56
	v_add_f32_e32 v57, 1.0, v57
	v_rcp_f32_e32 v59, v50
	v_add_f32_e32 v50, 1.0, v52
	v_mul_f32_e32 v42, 0xbfb8aa3b, v42
	v_rcp_f32_e32 v54, v54
	v_rcp_f32_e32 v55, v55
	v_rcp_f32_e32 v56, v56
	v_rcp_f32_e32 v57, v57
	v_rcp_f32_e32 v60, v50
	v_exp_f32_e32 v42, v42
	v_mul_f32_e32 v43, 0xbfb8aa3b, v43
	v_exp_f32_e32 v43, v43
	v_cvt_pk_bf16_f32 v50, v54, v55
	v_cvt_pk_bf16_f32 v51, v56, v57
	v_cvt_pk_bf16_f32 v52, v58, v53
	v_cvt_pk_bf16_f32 v53, v59, v60
	v_mul_f32_e32 v46, 0xbfb8aa3b, v46
	v_mul_f32_e32 v47, 0xbfb8aa3b, v47
	v_add_f32_e32 v42, 1.0, v42
	global_store_dwordx4 v[62:63], v[50:53], off offset:256
	v_exp_f32_e32 v46, v46
	v_exp_f32_e32 v47, v47
	v_rcp_f32_e32 v51, v42
	v_add_f32_e32 v42, 1.0, v43
	v_mul_f32_e32 v43, 0xbfb8aa3b, v44
	v_mul_f32_e32 v48, 0xbfb8aa3b, v48
	v_mul_f32_e32 v49, 0xbfb8aa3b, v49
	v_exp_f32_e32 v43, v43
	v_mul_f32_e32 v44, 0xbfb8aa3b, v45
	v_exp_f32_e32 v48, v48
	v_exp_f32_e32 v49, v49
	v_exp_f32_e32 v44, v44
	v_add_f32_e32 v46, 1.0, v46
	v_add_f32_e32 v47, 1.0, v47
	v_rcp_f32_e32 v46, v46
	v_rcp_f32_e32 v47, v47
	v_rcp_f32_e32 v45, v42
	v_add_f32_e32 v42, 1.0, v43
	v_add_f32_e32 v48, 1.0, v48
	v_add_f32_e32 v49, 1.0, v49
	v_rcp_f32_e32 v52, v42
	v_add_f32_e32 v42, 1.0, v44
	v_mul_f32_e32 v34, 0xbfb8aa3b, v34
	v_rcp_f32_e32 v48, v48
	v_rcp_f32_e32 v49, v49
	v_rcp_f32_e32 v53, v42
	v_exp_f32_e32 v34, v34
	v_mul_f32_e32 v35, 0xbfb8aa3b, v35
	v_exp_f32_e32 v35, v35
	v_cvt_pk_bf16_f32 v42, v46, v47
	v_cvt_pk_bf16_f32 v43, v48, v49
	v_cvt_pk_bf16_f32 v44, v51, v45
	v_cvt_pk_bf16_f32 v45, v52, v53
	s_mov_b32 s16, 0xd8000
	s_mov_b32 s17, 0
	v_lshl_add_u64 v[46:47], s[16:17], 0, v[128:129]
	v_add_f32_e32 v34, 1.0, v34
	global_store_dwordx4 v[46:47], v[42:45], off
	v_mul_f32_e32 v38, 0xbfb8aa3b, v38
	v_mul_f32_e32 v39, 0xbfb8aa3b, v39
	v_rcp_f32_e32 v42, v34
	v_add_f32_e32 v34, 1.0, v35
	v_mul_f32_e32 v35, 0xbfb8aa3b, v36
	v_mul_f32_e32 v40, 0xbfb8aa3b, v40
	v_mul_f32_e32 v41, 0xbfb8aa3b, v41
	v_exp_f32_e32 v35, v35
	v_mul_f32_e32 v36, 0xbfb8aa3b, v37
	v_exp_f32_e32 v38, v38
	v_exp_f32_e32 v39, v39
	v_exp_f32_e32 v40, v40
	v_exp_f32_e32 v41, v41
	v_exp_f32_e32 v36, v36
	v_rcp_f32_e32 v37, v34
	v_add_f32_e32 v34, 1.0, v35
	v_add_f32_e32 v38, 1.0, v38
	v_add_f32_e32 v39, 1.0, v39
	v_add_f32_e32 v40, 1.0, v40
	v_add_f32_e32 v41, 1.0, v41
	v_rcp_f32_e32 v43, v34
	v_add_f32_e32 v34, 1.0, v36
	v_mul_f32_e32 v26, 0xbfb8aa3b, v26
	v_rcp_f32_e32 v38, v38
	v_rcp_f32_e32 v39, v39
	v_rcp_f32_e32 v40, v40
	v_rcp_f32_e32 v41, v41
	v_rcp_f32_e32 v44, v34
	v_exp_f32_e32 v26, v26
	v_mul_f32_e32 v27, 0xbfb8aa3b, v27
	v_exp_f32_e32 v27, v27
	v_cvt_pk_bf16_f32 v34, v38, v39
	v_cvt_pk_bf16_f32 v35, v40, v41
	v_cvt_pk_bf16_f32 v36, v42, v37
	v_cvt_pk_bf16_f32 v37, v43, v44
	v_mul_f32_e32 v30, 0xbfb8aa3b, v30
	v_mul_f32_e32 v31, 0xbfb8aa3b, v31
	v_add_f32_e32 v26, 1.0, v26
	global_store_dwordx4 v[46:47], v[34:37], off offset:256
	v_exp_f32_e32 v30, v30
	v_exp_f32_e32 v31, v31
	v_rcp_f32_e32 v35, v26
	v_add_f32_e32 v26, 1.0, v27
	v_mul_f32_e32 v27, 0xbfb8aa3b, v28
	v_mul_f32_e32 v32, 0xbfb8aa3b, v32
	v_mul_f32_e32 v33, 0xbfb8aa3b, v33
	v_exp_f32_e32 v27, v27
	v_mul_f32_e32 v28, 0xbfb8aa3b, v29
	v_exp_f32_e32 v32, v32
	v_exp_f32_e32 v33, v33
	v_exp_f32_e32 v28, v28
	v_add_f32_e32 v30, 1.0, v30
	v_add_f32_e32 v31, 1.0, v31
	v_rcp_f32_e32 v30, v30
	v_rcp_f32_e32 v31, v31
	v_rcp_f32_e32 v29, v26
	v_add_f32_e32 v26, 1.0, v27
	v_add_f32_e32 v32, 1.0, v32
	v_add_f32_e32 v33, 1.0, v33
	v_rcp_f32_e32 v36, v26
	v_add_f32_e32 v26, 1.0, v28
	v_mul_f32_e32 v18, 0xbfb8aa3b, v18
	v_rcp_f32_e32 v32, v32
	v_rcp_f32_e32 v33, v33
; #define PG8_BAR __builtin_amdgcn_s_barrier()
; #define EPI8(...) \
;     _Pragma("unroll") for (int ai = 0; ai < 2; ++ai) _Pragma("unroll") for (int m = 0; m < 4; ++m) { const int row = u.pm * 256 + ai * 128 + wr * 64 + m * 16 + fr; \
;     _Pragma("unroll") for (int bj = 0; bj < 2; ++bj) { const int c8 = bj * 128 + wc * 32 + fq * 8; const f32x4 v0 = acc[ai][bj][m][0], v1 = acc[ai][bj][m][1]; __VA_ARGS__ } }
; __device__ __forceinline__ u32x4v pack8(f32x4 a, f32x4 b) { u32x4v o; o.x = cvt_pk_bf16(a[0], a[1]); o.y = cvt_pk_bf16(a[2], a[3]); o.z = cvt_pk_bf16(b[0], b[1]); o.w = cvt_pk_bf16(b[2], b[3]); return o; }
; __device__ __forceinline__ f32x4 sig4(f32x4 v) { return (f32x4){sigm(v[0]), sigm(v[1]), sigm(v[2]), sigm(v[3])}; }
; template <class Epi, class Sched, bool ALIGN_EPI = false, bool SP2 = false>
; __device__ __forceinline__ void gemm_phase(PG8_LAS unsigned char* lds, const Gemm g, const Sched& S, const Epi& E) {
;     ...
;         if constexpr (ALIGN_EPI) { if (wr == 0) PG8_BAR; }
;         if constexpr (!Epi::AFTER_DRAIN) { E(acc, cur, wr, wc, fr, fq); S.done(cur); }
;         if (!has_next) break;
; #pragma unroll
;         for (int a = 0; a < 2; ++a)
; #pragma unroll
;             for (int b = 0; b < 2; ++b)
; #pragma unroll
;                 for (int m = 0; m < 4; ++m)
; #pragma unroll
;                     for (int n = 0; n < 2; ++n) acc[a][b][m][n] = (f32x4){0.f, 0.f, 0.f, 0.f};
;         cur = nxt; cA = nA; cB = nB; ++ui;
;         if constexpr (ALIGN_EPI) { if (wr == 1) PG8_BAR; }
;     __device__ __forceinline__ void operator()(const f32x4 (&acc)[2][2][4][2], const pg8::Unit& u, int wr, int wc, int fr, int fq) const {
;         EPI8( *(u32x4v*)(O + (size_t)row * ldc + u.pn * 256 + c8) = pack8(sig4(v0), sig4(v1)); )
;     }
	v_rcp_f32_e32 v37, v26
	v_exp_f32_e32 v18, v18
	v_mul_f32_e32 v19, 0xbfb8aa3b, v19
	v_exp_f32_e32 v19, v19
	v_cvt_pk_bf16_f32 v26, v30, v31
	v_cvt_pk_bf16_f32 v27, v32, v33
	v_cvt_pk_bf16_f32 v28, v35, v29
	v_cvt_pk_bf16_f32 v29, v36, v37
	s_mov_b32 s16, 0xf0000
	s_mov_b32 s17, 0
	v_lshl_add_u64 v[30:31], s[16:17], 0, v[128:129]
	v_add_f32_e32 v18, 1.0, v18
	global_store_dwordx4 v[30:31], v[26:29], off
	v_mul_f32_e32 v22, 0xbfb8aa3b, v22
	v_mul_f32_e32 v23, 0xbfb8aa3b, v23
	v_rcp_f32_e32 v26, v18
	v_add_f32_e32 v18, 1.0, v19
	v_mul_f32_e32 v19, 0xbfb8aa3b, v20
	v_mul_f32_e32 v24, 0xbfb8aa3b, v24
	v_mul_f32_e32 v25, 0xbfb8aa3b, v25
	v_exp_f32_e32 v19, v19
	v_mul_f32_e32 v20, 0xbfb8aa3b, v21
	v_exp_f32_e32 v22, v22
	v_exp_f32_e32 v23, v23
	v_exp_f32_e32 v24, v24
	v_exp_f32_e32 v25, v25
	v_exp_f32_e32 v20, v20
	v_rcp_f32_e32 v21, v18
	v_add_f32_e32 v18, 1.0, v19
	v_add_f32_e32 v22, 1.0, v22
	v_add_f32_e32 v23, 1.0, v23
	v_add_f32_e32 v24, 1.0, v24
	v_add_f32_e32 v25, 1.0, v25
	v_rcp_f32_e32 v27, v18
	v_add_f32_e32 v18, 1.0, v20
	v_mul_f32_e32 v10, 0xbfb8aa3b, v10
	v_rcp_f32_e32 v22, v22
	v_rcp_f32_e32 v23, v23
	v_rcp_f32_e32 v24, v24
	v_rcp_f32_e32 v25, v25
	v_rcp_f32_e32 v28, v18
	v_exp_f32_e32 v10, v10
	v_mul_f32_e32 v11, 0xbfb8aa3b, v11
	v_exp_f32_e32 v11, v11
	v_cvt_pk_bf16_f32 v18, v22, v23
	v_cvt_pk_bf16_f32 v19, v24, v25
	v_cvt_pk_bf16_f32 v20, v26, v21
	v_cvt_pk_bf16_f32 v21, v27, v28
	v_mul_f32_e32 v14, 0xbfb8aa3b, v14
	v_mul_f32_e32 v15, 0xbfb8aa3b, v15
	v_add_f32_e32 v10, 1.0, v10
	global_store_dwordx4 v[30:31], v[18:21], off offset:256
	v_exp_f32_e32 v14, v14
	v_exp_f32_e32 v15, v15
	v_rcp_f32_e32 v19, v10
	v_add_f32_e32 v10, 1.0, v11
	v_mul_f32_e32 v11, 0xbfb8aa3b, v12
	v_mul_f32_e32 v16, 0xbfb8aa3b, v16
	v_mul_f32_e32 v17, 0xbfb8aa3b, v17
	v_exp_f32_e32 v11, v11
	v_mul_f32_e32 v12, 0xbfb8aa3b, v13
	v_exp_f32_e32 v16, v16
	v_exp_f32_e32 v17, v17
	v_exp_f32_e32 v12, v12
	v_add_f32_e32 v14, 1.0, v14
	v_add_f32_e32 v15, 1.0, v15
	v_rcp_f32_e32 v14, v14
	v_rcp_f32_e32 v15, v15
	v_rcp_f32_e32 v13, v10
	v_add_f32_e32 v10, 1.0, v11
	v_add_f32_e32 v16, 1.0, v16
	v_add_f32_e32 v17, 1.0, v17
	v_rcp_f32_e32 v20, v10
	v_add_f32_e32 v10, 1.0, v12
	v_mul_f32_e32 v2, 0xbfb8aa3b, v2
	v_rcp_f32_e32 v16, v16
	v_rcp_f32_e32 v17, v17
	v_rcp_f32_e32 v21, v10
	v_exp_f32_e32 v2, v2
	v_mul_f32_e32 v3, 0xbfb8aa3b, v3
	v_exp_f32_e32 v3, v3
	v_cvt_pk_bf16_f32 v10, v14, v15
	v_cvt_pk_bf16_f32 v11, v16, v17
	v_cvt_pk_bf16_f32 v12, v19, v13
	v_cvt_pk_bf16_f32 v13, v20, v21
	s_mov_b32 s16, 0x108000
	s_mov_b32 s17, 0
	v_lshl_add_u64 v[14:15], s[16:17], 0, v[128:129]
	v_add_f32_e32 v2, 1.0, v2
	global_store_dwordx4 v[14:15], v[10:13], off
	v_mul_f32_e32 v6, 0xbfb8aa3b, v6
	v_mul_f32_e32 v7, 0xbfb8aa3b, v7
	v_rcp_f32_e32 v10, v2
	v_add_f32_e32 v2, 1.0, v3
	v_mul_f32_e32 v3, 0xbfb8aa3b, v4
	v_mul_f32_e32 v8, 0xbfb8aa3b, v8
	v_mul_f32_e32 v9, 0xbfb8aa3b, v9
	v_exp_f32_e32 v3, v3
	v_mul_f32_e32 v4, 0xbfb8aa3b, v5
	v_exp_f32_e32 v6, v6
	v_exp_f32_e32 v7, v7
	v_exp_f32_e32 v8, v8
	v_exp_f32_e32 v9, v9
	v_exp_f32_e32 v4, v4
	v_rcp_f32_e32 v5, v2
	v_add_f32_e32 v2, 1.0, v3
	v_add_f32_e32 v6, 1.0, v6
	v_add_f32_e32 v7, 1.0, v7
	v_add_f32_e32 v8, 1.0, v8
	v_add_f32_e32 v9, 1.0, v9
	v_rcp_f32_e32 v11, v2
	v_add_f32_e32 v2, 1.0, v4
	v_rcp_f32_e32 v6, v6
	v_rcp_f32_e32 v7, v7
	v_rcp_f32_e32 v8, v8
	v_rcp_f32_e32 v9, v9
	v_rcp_f32_e32 v12, v2
	v_readlane_b32 s30, v254, 5
	v_cvt_pk_bf16_f32 v2, v6, v7
	v_cvt_pk_bf16_f32 v3, v8, v9
	v_cvt_pk_bf16_f32 v4, v10, v5
	v_cvt_pk_bf16_f32 v5, v11, v12
	s_andn2_b64 vcc, exec, s[0:1]
	s_mov_b64 s[0:1], -1
	v_readlane_b32 s31, v254, 6
	s_movk_i32 s34, 0x4000
	s_mov_b32 s35, 0x8000
	s_mov_b32 s36, 0xf149f2ca
	s_mov_b32 s38, 0x358637bd
	global_store_dwordx4 v[14:15], v[2:5], off offset:256
	s_cbranch_vccnz .LBB0_1242
	s_andn2_b64 vcc, exec, s[2:3]
	s_cbranch_vccnz .LBB0_1241
	s_barrier
	s_branch .LBB0_1241
